# phases 2/3 under attention plus attention-unit prologue de-serialisation: tile 1 co-fetched with tile 0 in the diff, selected and window branches, interleaved radix top-k select
# speedup vs baseline: 1.0202x; 1.0078x over previous
; #define NEG_INF (-__builtin_inff())
;     constexpr int SB = KT_BYTES + (HAS_V ? DV * VP : 0);
;     KVStage<DV> st;
;     int jn = j0;
;     if (probe != 1) { kv_gload<DV, HAS_V>(st, Kb, VTb, ldv, jn * 64); kv_sstore<DV, HAS_V>(st, lds); }
;     __syncthreads();
;     int tid_ = threadIdx.x; asm volatile("" : "+v"(tid_));
;     const int lane = tid_ & 63, w = tid_ >> 6, r = lane & 31, h = lane >> 5;
;     const int qt = 63 - (u >> 4), bg = u & 15, b = bg >> 1, g = bg & 1;
;     const int hq = w >> 2, q0 = qt * 64, qb = q0 + 32 * hq, qpos = qb + r, head = g * 4 + (w & 3);
;     float* IMPW = (float*)(lds + NSA_IMPW);
;     u64* SEL = (u64*)(lds + NSA_SEL);
;     u64* UN = (u64*)(lds + NSA_UN);
;     const bf16_t* Qb = (const bf16_t*)(p.ws + OFF_QN) + ((size_t)(b * 8 + head) * 4096) * 64;
;     bf16x8 qf[4];
; #pragma unroll
;     for (int s = 0; s < 4; ++s) qf[s] = *(const bf16x8*)(Qb + (size_t)qpos * 64 + s * 16 + h * 8);
; #pragma unroll
;     for (int s = 0; s < 4; ++s) asm volatile("" : "+v"(qf[s]));
;     const float* gp = (const float*)(p.ws + OFF_GATES) + ((size_t)b * 4096 + qpos) * 24 + head * 3;
;     auto inc = [](int j) { return j + 1; };
;     f32x16 oacc[2];
;     float* FT = (float*)(lds + NSA_FT);
;     {
;         const bf16_t* Kc = (const bf16_t*)(p.ws + OFF_KCMP) + (size_t)bg * 256 * 64;
;         const bf16_t* VcT = (const bf16_t*)(p.ws + OFF_VCMPT) + (size_t)bg * 64 * 256;
;         const int nmax = ((q0 + 32) >> 4) + 1, ntc = (nmax + 63) >> 6;
;         const int nvalid = qpos >= 31 ? ((qpos - 31) >> 4) + 1 : 0;
;         float m = -1e30f, l = 0.f, carry = 0.f;
;         f32x16 oc[2];
; #pragma unroll
;         for (int dt = 0; dt < 2; ++dt)
; #pragma unroll
;             for (int i = 0; i < 16; ++i) oc[dt][i] = 0.f;
;         kv_loop<64, true>(lds, Kc, VcT, 256, ntc, 0, inc, [&](int j, const unsigned char* sb) {
;             f32x16 s0, s1; attn_scores(sb, qf, r, h, s0, s1);
;             float mx = NEG_INF;
; #pragma unroll
.LBB0_490:
	s_or_b64 exec, exec, s[4:5]
	s_cmp_lg_u32 s33, -1
	s_cselect_b32 s2, s33, 0
	s_cselect_b32 s3, s71, 0
	v_mov_b32_e32 v2, s2
	v_mov_b32_e32 v3, s3
	s_waitcnt lgkmcnt(0)
	s_barrier
	flat_load_dword v2, v[2:3] sc0 sc1
	s_waitcnt vmcnt(0)
	s_movk_i32 s2, 0x400
	s_mov_b64 s[4:5], -1
	s_waitcnt lgkmcnt(0)
	s_barrier
	v_cmp_gt_i32_e32 vcc, s2, v2
	s_and_saveexec_b64 s[94:95], vcc
	s_cbranch_execz .LBB0_485
	v_mov_b32_e32 v17, v1
	v_lshlrev_b32_e32 v3, 2, v2
	v_ashrrev_i32_e32 v82, 6, v17
	v_and_b32_e32 v130, 0xffffffc0, v3
	v_lshlrev_b32_e32 v83, 3, v82
	v_sub_u32_e32 v123, 0xfc0, v130
	v_and_b32_e32 v81, 0xffffffe0, v83
	v_and_b32_e32 v80, 31, v17
	v_bfe_u32 v85, v2, 1, 3
	v_add_u32_e32 v203, v81, v123
	v_and_b32_e32 v3, 4, v3
	v_or_b32_e32 v178, v203, v80
	v_and_or_b32 v202, v82, 3, v3
	v_lshlrev_b32_e32 v3, 22, v85
	v_readlane_b32 s2, v238, 47
	v_lshl_or_b32 v4, v202, 19, v3
	v_mov_b32_e32 v5, v173
	v_readlane_b32 s3, v238, 48
	v_ashrrev_i32_e32 v179, 31, v178
	v_bfe_u32 v36, v17, 5, 1
	v_lshl_add_u64 v[4:5], s[2:3], 0, v[4:5]
	v_lshlrev_b64 v[6:7], 7, v[178:179]
	v_lshl_add_u64 v[4:5], v[4:5], 0, v[6:7]
	v_lshlrev_b32_e32 v180, 4, v36
	v_mov_b32_e32 v181, v173
	v_lshl_add_u64 v[4:5], v[4:5], 0, v[180:181]
	global_load_dwordx4 v[146:149], v[4:5], off
	global_load_dwordx4 v[150:153], v[4:5], off offset:32
	global_load_dwordx4 v[154:157], v[4:5], off offset:64
	global_load_dwordx4 v[158:161], v[4:5], off offset:96
	v_and_b32_e32 v122, 15, v2
	v_readlane_b32 s2, v238, 49
	v_mov_b32_e32 v3, v173
	v_lshlrev_b32_e32 v2, 15, v122
	v_readlane_b32 s3, v238, 50
	v_lshl_add_u64 v[74:75], v[176:177], 0, v[2:3]
	v_and_b32_e32 v84, 63, v17
	v_lshl_add_u64 v[34:35], s[2:3], 0, v[2:3]
	v_lshl_add_u64 v[2:3], v[34:35], 0, v[170:171]
	v_lshl_add_u64 v[2:3], v[2:3], 0, v[172:173]
	v_lshrrev_b32_e32 v17, 4, v123
	v_add_u32_e32 v17, 64, v17
	v_lshrrev_b32_e32 v90, 6, v17
	v_subrev_u32_e32 v17, 31, v178
	v_ashrrev_i32_e32 v17, 4, v17
	v_mov_b32_e32 v88, 0
	v_lshl_add_u64 v[76:77], v[34:35], 0, v[172:173]
	v_lshlrev_b32_e32 v181, 2, v36
	v_lshl_add_u32 v34, v82, 13, 0
	v_lshlrev_b32_e32 v35, 8, v80
	v_lshlrev_b32_e32 v36, 4, v80
	v_lshlrev_b32_e32 v37, 9, v82
	v_add_u32_e32 v17, 1, v17
	v_cmp_lt_i32_e32 vcc, 30, v178
	v_mov_b32_e32 v93, 0xf149f2ca
	s_mov_b64 s[72:73], 0
	s_mov_b32 s2, 0
	v_mov_b32_e32 v92, 0
	v_mov_b32_e32 v94, 0
	v_mov_b32_e32 v18, 0
	v_mov_b32_e32 v19, v88
	v_mov_b32_e32 v20, v88
	v_mov_b32_e32 v21, v88
	v_mov_b32_e32 v22, v88
	v_mov_b32_e32 v23, v88
	v_mov_b32_e32 v24, v88
	v_mov_b32_e32 v25, v88
	v_mov_b32_e32 v26, v88
	v_mov_b32_e32 v27, v88
	v_mov_b32_e32 v28, v88
	v_mov_b32_e32 v29, v88
	v_mov_b32_e32 v30, v88
	v_mov_b32_e32 v31, v88
	v_mov_b32_e32 v32, v88
	v_mov_b32_e32 v33, v88
	v_mov_b32_e32 v4, v88
	v_mov_b32_e32 v5, v88
	v_mov_b32_e32 v6, v88
	v_mov_b32_e32 v7, v88
	v_mov_b32_e32 v8, v88
	v_mov_b32_e32 v9, v88
	v_mov_b32_e32 v10, v88
	v_mov_b32_e32 v11, v88
	v_mov_b32_e32 v12, v88
	v_mov_b32_e32 v13, v88
	v_mov_b32_e32 v14, v88
	v_mov_b32_e32 v15, v88
	v_mov_b32_e32 v16, v88
	v_mul_u32_u24_e32 v204, 0x90, v80
	global_load_dwordx4 v[66:69], v[2:3], off
	global_load_dwordx4 v[70:73], v[74:75], off
	v_mov_b32_e32 v2, 0
	v_mov_b32_e32 v3, v88
	v_cmp_gt_u32_e64 s[66:67], 32, v84
	v_mul_u32_u24_e32 v86, 3, v202
	v_add3_u32 v89, v34, v35, v181
	v_add3_u32 v87, s74, v36, v37
	v_cndmask_b32_e32 v91, 0, v17, vcc
	v_mov_b32_e32 v17, v88
	s_waitcnt vmcnt(1)
	ds_write_b128 v198, v[66:69]
	s_waitcnt vmcnt(0)
	ds_write2_b64 v199, v[70:71], v[72:73] offset0:128 offset1:130
	s_waitcnt lgkmcnt(0)
	s_barrier
	s_branch .LBB0_493

; template <int DV, bool HAS_V>
; DI void kv_gload(KVStage<DV>& st, const bf16_t* __restrict__ Kb, const bf16_t* __restrict__ VTb, int ldv, int key0) {
;     const int tid = threadIdx.x;
;     st.k[0] = *(const u32x4*)(Kb + (size_t)(key0 + (tid >> 3)) * 64 + (tid & 7) * 8);
;     if (HAS_V) {
; #pragma unroll
;         for (int i = 0; i < DV / 64; ++i) { const int c = tid + 512 * i; st.v[i] = *(const u32x4*)(VTb + (size_t)(key0 >> 6) * (DV * 64) + c * 8); }
;     }
; }
;     ...
;     const u64 mysel = SEL[32 * hq + r];
;     const u64 U = ((UN[0] | UN[1]) | (UN[2] | UN[3])) | ((UN[4] | UN[5]) | (UN[6] | UN[7]));
;     {
;         const bf16_t* Ks = (const bf16_t*)(p.ws + OFF_KS) + (size_t)bg * 4096 * 64;
;         const bf16_t* VsT = (const bf16_t*)(p.ws + OFF_VST) + (size_t)bg * 64 * 4096;
;         const int nts = __popcll(U), j0 = __ffsll((long long)U) - 1;
;         f32x16 o[2];
; #pragma unroll
;         for (int dt = 0; dt < 2; ++dt)
; #pragma unroll
;             for (int i = 0; i < 16; ++i) o[dt][i] = 0.f;
;         float m = -1e30f; f32x16 lv;
; #pragma unroll
;         for (int i = 0; i < 16; ++i) lv[i] = 0.f;
;         kv_loop<64, true>(lds, Ks, VsT, 4096, nts, j0, [U](int j) { return __ffsll((long long)(U & (~0ull << (j + 1)))) - 1; }, [&](int j, const unsigned char* sb) {
.LBB0_538:
	s_or_b64 exec, exec, s[4:5]
	v_readlane_b32 s3, v238, 55
	s_add_i32 s2, 0, 0x19200
	s_waitcnt lgkmcnt(0)
	v_mov_b32_e32 v34, s3
	s_barrier
	ds_read_b128 v[34:37], v34
	v_mov_b32_e32 v38, s2
	ds_read_b128 v[38:41], v38
	v_readlane_b32 s2, v238, 56
	v_readlane_b32 s6, v238, 57
	s_waitcnt lgkmcnt(1)
	v_readfirstlane_b32 s3, v35
	v_mov_b32_e32 v42, s2
	ds_read_b128 v[42:45], v42
	v_readfirstlane_b32 s2, v34
	v_mov_b32_e32 v34, s6
	v_readfirstlane_b32 s5, v37
	v_readfirstlane_b32 s4, v36
	ds_read_b128 v[34:37], v34
	s_waitcnt lgkmcnt(2)
	v_readfirstlane_b32 s15, v39
	v_readfirstlane_b32 s14, v38
	v_readfirstlane_b32 s17, v41
	v_readfirstlane_b32 s16, v40
	s_or_b64 s[14:15], s[16:17], s[14:15]
	s_or_b64 s[2:3], s[14:15], s[2:3]
	s_waitcnt lgkmcnt(1)
	v_readfirstlane_b32 s7, v43
	v_readfirstlane_b32 s6, v42
	s_or_b64 s[2:3], s[2:3], s[4:5]
	v_readfirstlane_b32 s9, v45
	v_readfirstlane_b32 s8, v44
	s_or_b64 s[2:3], s[2:3], s[6:7]
	s_waitcnt lgkmcnt(0)
	v_readfirstlane_b32 s11, v35
	v_readfirstlane_b32 s10, v34
	s_or_b64 s[2:3], s[2:3], s[8:9]
	v_readfirstlane_b32 s13, v37
	v_readfirstlane_b32 s12, v36
	s_or_b64 s[2:3], s[2:3], s[10:11]
	v_lshlrev_b32_e32 v34, 3, v81
	v_lshlrev_b32_e32 v35, 3, v80
	s_or_b64 s[6:7], s[2:3], s[12:13]
	v_readlane_b32 s2, v238, 53
	v_add3_u32 v34, s75, v34, v35
	v_lshlrev_b32_e32 v36, 19, v122
	v_mov_b32_e32 v37, v173
	v_readlane_b32 s3, v238, 54
	s_cmp_eq_u64 s[6:7], 0
	ds_read_b64 v[124:125], v34
	v_lshl_add_u64 v[34:35], s[2:3], 0, v[36:37]
	s_cselect_b64 s[2:3], -1, 0
	s_ff1_i32_b64 s12, s[6:7]
	s_and_b64 vcc, s[2:3], exec
	s_cselect_b32 s2, -1, s12
	v_lshl_add_u32 v38, s2, 6, v187
	v_readlane_b32 s4, v238, 51
	v_ashrrev_i32_e32 v39, 31, v38
	v_readlane_b32 s5, v238, 52
	v_lshlrev_b64 v[38:39], 7, v[38:39]
	s_ashr_i32 s3, s2, 31
	v_lshl_add_u64 v[36:37], s[4:5], 0, v[36:37]
	v_lshl_add_u64 v[38:39], v[34:35], 0, v[38:39]
	s_lshl_b64 s[2:3], s[2:3], 13
	v_lshl_add_u64 v[38:39], v[38:39], 0, v[172:173]
	v_lshl_add_u64 v[40:41], v[36:37], 0, s[2:3]
	v_mov_b32_e32 v175, v173
	v_lshl_add_u64 v[40:41], v[40:41], 0, v[174:175]
	global_load_dwordx4 v[114:117], v[38:39], off
	global_load_dwordx4 v[118:121], v[40:41], off
	s_lshl_b64 s[42:43], 2, s12
	s_sub_u32 s42, s42, 1
	s_subb_u32 s43, s43, 0
	s_andn2_b64 s[42:43], s[6:7], s[42:43]
	s_cmp_eq_u64 s[42:43], 0
	s_cbranch_scc1 .Lns_pf_skip
	s_ff1_i32_b64 s44, s[42:43]
	s_lshl_b32 s45, s44, 6
	v_add_u32_e32 v232, s45, v187
	v_mov_b32_e32 v233, v173
	v_lshlrev_b64 v[232:233], 7, v[232:233]
	v_lshl_add_u64 v[232:233], v[34:35], 0, v[232:233]
	v_lshl_add_u64 v[232:233], v[232:233], 0, v[172:173]
	global_load_dwordx4 v[224:227], v[232:233], off
	s_lshl_b32 s46, s44, 13
	s_mov_b32 s47, 0
	v_lshl_add_u64 v[234:235], v[36:37], 0, s[46:47]
	v_lshl_add_u64 v[234:235], v[234:235], 0, v[174:175]
	global_load_dwordx4 v[228:231], v[234:235], off
.Lns_pf_skip:

;     constexpr int SB = KT_BYTES + (HAS_V ? DV * VP : 0);
;     KVStage<DV> st;
;     int jn = j0;
;     if (probe != 1) { kv_gload<DV, HAS_V>(st, Kb, VTb, ldv, jn * 64); kv_sstore<DV, HAS_V>(st, lds); }
;     __syncthreads();
;     ...
;     {
;         const bf16_t* Ks = (const bf16_t*)(p.ws + OFF_KS) + (size_t)bg * 4096 * 64;
;         const bf16_t* VsT = (const bf16_t*)(p.ws + OFF_VST) + (size_t)bg * 64 * 4096;
;         const int nts = __popcll(U), j0 = __ffsll((long long)U) - 1;
;         f32x16 o[2];
; #pragma unroll
;         for (int dt = 0; dt < 2; ++dt)
; #pragma unroll
;             for (int i = 0; i < 16; ++i) o[dt][i] = 0.f;
;         float m = -1e30f; f32x16 lv;
; #pragma unroll
;         for (int i = 0; i < 16; ++i) lv[i] = 0.f;
	s_waitcnt vmcnt(1)
	ds_write_b128 v198, v[114:117]
	s_waitcnt vmcnt(0)
	ds_write2_b64 v199, v[118:119], v[120:121] offset0:128 offset1:130
	s_waitcnt lgkmcnt(0)
	s_barrier
	s_cbranch_vccnz .LBB0_556
	v_lshl_add_u64 v[126:127], v[34:35], 0, v[172:173]
	v_and_b32_e32 v34, 0xffffffc0, v203
	v_mov_b32_e32 v48, v173
	v_mov_b32_e32 v49, v173
	v_lshl_add_u64 v[128:129], v[36:37], 0, v[174:175]
	v_sub_u32_e32 v206, v178, v34
	v_mov_b32_e32 v34, v173
	v_mov_b32_e32 v35, v173
	v_mov_b32_e32 v36, v173
	v_mov_b32_e32 v37, v173
	v_mov_b32_e32 v38, v173
	v_mov_b32_e32 v39, v173
	v_mov_b32_e32 v40, v173
	v_mov_b32_e32 v41, v173
	v_mov_b32_e32 v42, v173
	v_mov_b32_e32 v43, v173
	v_mov_b32_e32 v44, v173
	v_mov_b32_e32 v45, v173
	v_mov_b32_e32 v46, v173
	v_mov_b32_e32 v47, v173
	v_mov_b64_e32 v[64:65], v[48:49]
	v_mov_b64_e32 v[80:81], v[48:49]
	s_bcnt1_i32_b64 s2, s[6:7]
	v_ashrrev_i32_e32 v131, 6, v203
	v_or_b32_e32 v132, 32, v181
	v_or_b32_e32 v133, 33, v181
	v_or_b32_e32 v134, 2, v181
	v_or_b32_e32 v135, 34, v181
	v_or_b32_e32 v136, 3, v181
	v_or_b32_e32 v137, 35, v181
	v_or_b32_e32 v138, 8, v181
	v_or_b32_e32 v139, 40, v181
	v_or_b32_e32 v140, 9, v181
	v_or_b32_e32 v141, 41, v181
	v_or_b32_e32 v142, 10, v181
	v_or_b32_e32 v143, 42, v181
	v_or_b32_e32 v144, 11, v181
	v_or_b32_e32 v145, 43, v181
	v_or_b32_e32 v162, 16, v181
	v_or_b32_e32 v163, 48, v181
	v_or_b32_e32 v164, 17, v181
	v_or_b32_e32 v165, 49, v181
	v_or_b32_e32 v166, 18, v181
	v_or_b32_e32 v167, 50, v181
	v_or_b32_e32 v168, 19, v181
	v_or_b32_e32 v169, 51, v181
	v_or_b32_e32 v175, 24, v181
	v_or_b32_e32 v186, 56, v181
	v_or_b32_e32 v188, 25, v181
	v_or_b32_e32 v189, 57, v181
	v_or_b32_e32 v190, 26, v181
	v_or_b32_e32 v191, 58, v181
	v_or_b32_e32 v192, 27, v181
	v_or_b32_e32 v193, 59, v181
	s_mov_b32 s13, 0
	v_mov_b32_e32 v207, 0xf149f2ca
	v_mov_b64_e32 v[62:63], v[46:47]
	v_mov_b64_e32 v[60:61], v[44:45]
	v_mov_b64_e32 v[58:59], v[42:43]
	v_mov_b64_e32 v[56:57], v[40:41]
	v_mov_b64_e32 v[54:55], v[38:39]
	v_mov_b64_e32 v[52:53], v[36:37]
	v_mov_b64_e32 v[50:51], v[34:35]
	v_mov_b64_e32 v[78:79], v[46:47]
	v_mov_b64_e32 v[76:77], v[44:45]
	v_mov_b64_e32 v[74:75], v[42:43]
	v_mov_b64_e32 v[72:73], v[40:41]
	v_mov_b64_e32 v[70:71], v[38:39]
	v_mov_b64_e32 v[68:69], v[36:37]
	v_mov_b64_e32 v[66:67], v[34:35]
	global_load_dword v192, v[184:185], off offset:4
	v_readfirstlane_b32 s28, v0
	v_readfirstlane_b32 s21, v131
	s_bfe_u32 s28, s28, 0x10008
	s_mov_b32 s13, 0
	s_mov_b32 s18, 0
	s_movk_i32 s19, 0x4800
	s_mov_b32 s20, 0x9000
	s_mov_b32 s8, s12
	s_mov_b32 s9, s12
	s_mov_b32 s10, s12

;     ...
;             const bool mine = (mysel >> j) & 1ull;
	v_lshrrev_b64 v[168:169], s12, v[124:125]
	v_and_b32_e32 v168, 1, v168
	v_cmp_ne_u32_e64 s[14:15], 0, v168

;     ...
;     for (int i = 0; i < nt; ++i) {
;         const int j = jn;
;         const bool more = (i + 1 < nt);
;         if (more) { jn = next(j); if (probe != 1) kv_gload<DV, HAS_V>(st, Kb, VTb, ldv, jn * 64); }
	s_cmp_lt_u32 s2, 2
	s_cbranch_scc1 .Lns_p1

;     ...
;         kv_loop<64, true>(lds, Ks, VsT, 4096, nts, j0, [U](int j) { return __ffsll((long long)(U & (~0ull << (j + 1)))) - 1; }, [&](int j, const unsigned char* sb) {
	s_add_i32 s22, s12, 1
	s_lshl_b64 s[22:23], -1, s22
	s_and_b64 s[22:23], s[22:23], s[6:7]
	s_ff1_i32_b64 s8, s[22:23]

; template <int DV, bool HAS_V>
; DI void kv_sstore(const KVStage<DV>& st, unsigned char* buf) {
;     const int tid = threadIdx.x;
;     *(u32x4*)(buf + (tid >> 3) * KP + (tid & 7) * 16) = st.k[0];
;     if (HAS_V) {
; #pragma unroll
;         for (int i = 0; i < DV / 64; ++i) {
;             const int c = tid + 512 * i, kc = c & 7; unsigned char* q = buf + KT_BYTES + (c >> 3) * VP + (kc >> 1) * 32 + (kc & 1) * 8;
;             u32x2 lo, hi; lo.x = st.v[i].x; lo.y = st.v[i].y; hi.x = st.v[i].z; hi.y = st.v[i].w;
;             *(u32x2*)q = lo; *(u32x2*)(q + 16) = hi;
;         }
;     }
; }
	s_waitcnt vmcnt(0)
	v_add_u32_e32 v236, s19, v194
	v_add_u32_e32 v237, v236, v195
	v_add3_u32 v236, v236, v196, v197
	v_add_u32_e32 v236, 0x2000, v236
	ds_write_b128 v237, v[224:227]
	ds_write2_b64 v236, v[228:229], v[230:231] offset0:128 offset1:130

;     ...
;     for (int i = 0; i < nt; ++i) {
;         const int j = jn;
;         const bool more = (i + 1 < nt);
;         if (more) { jn = next(j); if (probe != 1) kv_gload<DV, HAS_V>(st, Kb, VTb, ldv, jn * 64); }
	s_cmp_lt_u32 s2, 3
	s_cbranch_scc1 .Lns_p1

;     ...
;         kv_loop<64, true>(lds, Ks, VsT, 4096, nts, j0, [U](int j) { return __ffsll((long long)(U & (~0ull << (j + 1)))) - 1; }, [&](int j, const unsigned char* sb) {
	s_add_i32 s22, s8, 1
	s_lshl_b64 s[22:23], -1, s22
	s_and_b64 s[22:23], s[22:23], s[6:7]
	s_ff1_i32_b64 s9, s[22:23]

; template <int DV, bool HAS_V>
; DI void kv_gload(KVStage<DV>& st, const bf16_t* __restrict__ Kb, const bf16_t* __restrict__ VTb, int ldv, int key0) {
;     const int tid = threadIdx.x;
;     st.k[0] = *(const u32x4*)(Kb + (size_t)(key0 + (tid >> 3)) * 64 + (tid & 7) * 8);
;     if (HAS_V) {
; #pragma unroll
;         for (int i = 0; i < DV / 64; ++i) { const int c = tid + 512 * i; st.v[i] = *(const u32x4*)(VTb + (size_t)(key0 >> 6) * (DV * 64) + c * 8); }
;     }
; }
	s_lshl_b32 s24, s9, 6
	v_add_u32_e32 v188, s24, v187
	v_mov_b32_e32 v189, v173
	v_lshlrev_b64 v[188:189], 7, v[188:189]
	v_lshl_add_u64 v[188:189], v[126:127], 0, v[188:189]
	global_load_dwordx4 v[114:117], v[188:189], off
	s_lshl_b32 s24, s9, 13
	s_mov_b32 s25, 0
	v_lshl_add_u64 v[190:191], v[128:129], 0, s[24:25]
	global_load_dwordx4 v[118:121], v[190:191], off

;     ...
;     for (int i = 0; i < nt; ++i) {
;         const int j = jn;
;         const bool more = (i + 1 < nt);
;         if (more) { jn = next(j); if (probe != 1) kv_gload<DV, HAS_V>(st, Kb, VTb, ldv, jn * 64); }
	s_cmp_lt_u32 s2, 4
	s_cbranch_scc1 .Lns_p1

;     ...
;         kv_loop<64, true>(lds, Ks, VsT, 4096, nts, j0, [U](int j) { return __ffsll((long long)(U & (~0ull << (j + 1)))) - 1; }, [&](int j, const unsigned char* sb) {
	s_add_i32 s22, s9, 1
	s_lshl_b64 s[22:23], -1, s22
	s_and_b64 s[22:23], s[22:23], s[6:7]
	s_ff1_i32_b64 s10, s[22:23]

;     ...
;             const bool mine = (mysel >> j) & 1ull;
;             if (__ballot(mine) != 0ull) {
;                 f32x16 s0, s1; attn_scores(sb, qf, r, h, s0, s1);
.Lns_p1:
	s_cmp_eq_u64 s[14:15], 0
	s_cbranch_scc1 .Lns_p3
	v_add3_u32 v144, s18, v204, v180

; #define MFMA(a, b, c) __builtin_amdgcn_mfma_f32_32x32x16_bf16((a), (b), (c), 0, 0, 0)
; DI void attn_scores(const unsigned char* kb, const bf16x8 (&qf)[4], int r, int h, f32x16& s0, f32x16& s1) {
; #pragma unroll
;     for (int i = 0; i < 16; ++i) { s0[i] = 0.f; s1[i] = 0.f; }
; #pragma unroll
;     for (int s = 0; s < 4; ++s) {
;         const bf16x8 k0 = *(const bf16x8*)(kb + r * KP + s * 32 + h * 16);
;         const bf16x8 k1 = *(const bf16x8*)(kb + (32 + r) * KP + s * 32 + h * 16);
;         s0 = MFMA(k0, qf[s], s0); s1 = MFMA(k1, qf[s], s1);
;     }
; }
	ds_read_b128 v[224:227], v144 offset:0
	ds_read_b128 v[228:231], v144 offset:4608
	ds_read_b128 v[232:235], v144 offset:32
	ds_read_b128 v[132:135], v144 offset:4640
	ds_read_b128 v[136:139], v144 offset:64
	ds_read_b128 v[140:143], v144 offset:4672
	s_waitcnt lgkmcnt(5)
	v_mfma_f32_32x32x16_bf16 v[98:113], v[224:227], v[146:149], 0
	ds_read_b128 v[224:227], v144 offset:96
	s_waitcnt lgkmcnt(5)
	v_mfma_f32_32x32x16_bf16 v[82:97], v[228:231], v[146:149], 0
	ds_read_b128 v[228:231], v144 offset:4704
	s_waitcnt lgkmcnt(5)
	v_mfma_f32_32x32x16_bf16 v[98:113], v[232:235], v[150:153], v[98:113]
	s_waitcnt lgkmcnt(4)
	v_mfma_f32_32x32x16_bf16 v[82:97], v[132:135], v[150:153], v[82:97]
	s_waitcnt lgkmcnt(3)
	v_mfma_f32_32x32x16_bf16 v[98:113], v[136:139], v[154:157], v[98:113]
	s_waitcnt lgkmcnt(2)
	v_mfma_f32_32x32x16_bf16 v[82:97], v[140:143], v[154:157], v[82:97]
	s_waitcnt lgkmcnt(1)
	v_mfma_f32_32x32x16_bf16 v[98:113], v[224:227], v[158:161], v[98:113]
	s_waitcnt lgkmcnt(0)
	v_mfma_f32_32x32x16_bf16 v[82:97], v[228:231], v[158:161], v[82:97]
.Lns_p3:
	s_waitcnt lgkmcnt(0)
	s_cmp_eq_u32 s28, 0
	s_cbranch_scc1 .Lns_loop
	s_barrier

; template <int DV, bool HAS_V>
; DI void kv_gload(KVStage<DV>& st, const bf16_t* __restrict__ Kb, const bf16_t* __restrict__ VTb, int ldv, int key0) {
;     const int tid = threadIdx.x;
;     st.k[0] = *(const u32x4*)(Kb + (size_t)(key0 + (tid >> 3)) * 64 + (tid & 7) * 8);
;     if (HAS_V) {
; #pragma unroll
;         for (int i = 0; i < DV / 64; ++i) { const int c = tid + 512 * i; st.v[i] = *(const u32x4*)(VTb + (size_t)(key0 >> 6) * (DV * 64) + c * 8); }
;     }
; }
;     ...
;         const bf16_t* Kw = (const bf16_t*)(p.ws + OFF_KW) + (size_t)bg * 4096 * 64;
;         const bf16_t* VwT = (const bf16_t*)(p.ws + OFF_VWT) + (size_t)bg * 64 * 4096;
;         const int tlo = (q0 > 511 ? q0 - 511 : 0) >> 6, thi = (q0 + 63) >> 6;
;         f32x16 o[2];
; #pragma unroll
;         for (int dt = 0; dt < 2; ++dt)
; #pragma unroll
;             for (int i = 0; i < 16; ++i) o[dt][i] = 0.f;
;         float m = -1e30f; f32x16 lv;
; #pragma unroll
;         for (int i = 0; i < 16; ++i) lv[i] = 0.f;
;         kv_loop<64, true>(lds, Kw, VwT, 4096, thi - tlo + 1, tlo, inc, [&](int j, const unsigned char* sb) {
.LBB0_559:
	s_or_b64 exec, exec, s[4:5]
	v_sub_u32_e32 v66, 0xdc0, v130
	s_movk_i32 s2, 0x1ff
	v_ashrrev_i32_e32 v66, 6, v66
	v_cmp_lt_i32_e32 vcc, s2, v123
	v_mov_b32_e32 v67, v173
	v_mov_b32_e32 v175, v173
	s_waitcnt vmcnt(1)
	v_cndmask_b32_e32 v114, 0, v66, vcc
	v_lshlrev_b32_e32 v66, 1, v82
	v_lshl_add_u64 v[116:117], s[96:97], 0, v[66:67]
	s_waitcnt vmcnt(0)
	v_lshl_add_u64 v[118:119], s[82:83], 0, v[66:67]
	v_lshl_add_u32 v66, v114, 6, v187
	v_ashrrev_i32_e32 v67, 31, v66
	v_lshlrev_b64 v[66:67], 7, v[66:67]
	v_ashrrev_i32_e32 v115, 31, v114
	v_lshl_add_u64 v[66:67], v[118:119], 0, v[66:67]
	v_lshlrev_b64 v[68:69], 13, v[114:115]
	v_lshl_add_u64 v[66:67], v[66:67], 0, v[172:173]
	v_lshl_add_u64 v[68:69], v[116:117], 0, v[68:69]
	v_lshl_add_u64 v[68:69], v[68:69], 0, v[174:175]
	global_load_dwordx4 v[162:165], v[66:67], off
	global_load_dwordx4 v[166:169], v[68:69], off
	s_mov_b64 s[42:43], 0x2000
	v_lshl_add_u64 v[236:237], v[66:67], 0, s[42:43]
	global_load_dwordx4 v[228:231], v[236:237], off
	v_lshl_add_u64 v[236:237], v[68:69], 0, s[42:43]
	global_load_dwordx4 v[232:235], v[236:237], off

;     constexpr int SB = KT_BYTES + (HAS_V ? DV * VP : 0);
;     KVStage<DV> st;
;     int jn = j0;
;     if (probe != 1) { kv_gload<DV, HAS_V>(st, Kb, VTb, ldv, jn * 64); kv_sstore<DV, HAS_V>(st, lds); }
;     __syncthreads();
;     ...
;         f32x16 o[2];
; #pragma unroll
;         for (int dt = 0; dt < 2; ++dt)
; #pragma unroll
;             for (int i = 0; i < 16; ++i) o[dt][i] = 0.f;
;         float m = -1e30f; f32x16 lv;
; #pragma unroll
;         for (int i = 0; i < 16; ++i) lv[i] = 0.f;
	v_lshrrev_b32_e32 v66, 6, v123
	v_mov_b32_e32 v98, v173
	v_mov_b32_e32 v99, v173
	v_mov_b32_e32 v100, v173
	v_mov_b32_e32 v101, v173
	v_mov_b32_e32 v102, v173
	v_mov_b32_e32 v103, v173
	v_mov_b32_e32 v104, v173
	v_mov_b32_e32 v105, v173
	v_mov_b32_e32 v106, v173
	v_mov_b32_e32 v107, v173
	v_mov_b32_e32 v108, v173
	v_mov_b32_e32 v109, v173
	v_mov_b32_e32 v110, v173
	v_mov_b32_e32 v111, v173
	v_mov_b32_e32 v112, v173
	v_mov_b32_e32 v113, v173
	v_mov_b64_e32 v[82:83], v[98:99]
	v_sub_u32_e32 v206, v66, v114
	v_mov_b64_e32 v[66:67], v[98:99]
	v_mov_b64_e32 v[84:85], v[100:101]
	v_mov_b64_e32 v[86:87], v[102:103]
	v_mov_b64_e32 v[88:89], v[104:105]
	v_mov_b64_e32 v[90:91], v[106:107]
	v_mov_b64_e32 v[92:93], v[108:109]
	v_mov_b64_e32 v[94:95], v[110:111]
	v_mov_b64_e32 v[96:97], v[112:113]
	v_cmp_lt_i32_e32 vcc, -1, v206
	v_mov_b64_e32 v[68:69], v[100:101]
	v_mov_b64_e32 v[70:71], v[102:103]
	v_mov_b64_e32 v[72:73], v[104:105]
	v_mov_b64_e32 v[74:75], v[106:107]
	v_mov_b64_e32 v[76:77], v[108:109]
	v_mov_b64_e32 v[78:79], v[110:111]
	v_mov_b64_e32 v[80:81], v[112:113]
	s_waitcnt vmcnt(1)
	ds_write_b128 v198, v[162:165]
	s_waitcnt vmcnt(0)
	ds_write2_b64 v199, v[166:167], v[168:169] offset0:128 offset1:130
	s_waitcnt lgkmcnt(0)
	s_barrier
	s_and_saveexec_b64 s[8:9], vcc
	s_cbranch_execz .LBB0_575
	v_mov_b32_e32 v80, v173
	v_mov_b32_e32 v81, v173
	v_mov_b32_e32 v66, v173
	v_mov_b32_e32 v67, v173
	v_mov_b32_e32 v68, v173
	v_mov_b32_e32 v69, v173
	v_mov_b32_e32 v70, v173
	v_mov_b32_e32 v71, v173
	v_mov_b32_e32 v72, v173
	v_mov_b32_e32 v73, v173
	v_mov_b32_e32 v74, v173
	v_mov_b32_e32 v75, v173
	v_mov_b32_e32 v76, v173
	v_mov_b32_e32 v77, v173
	v_mov_b32_e32 v78, v173
	v_mov_b32_e32 v79, v173
	v_mov_b64_e32 v[96:97], v[80:81]
	v_mov_b64_e32 v[112:113], v[80:81]
	v_lshl_add_u64 v[188:189], v[118:119], 0, v[172:173]
	v_lshl_add_u64 v[190:191], v[116:117], 0, v[174:175]
	v_or_b32_e32 v175, 31, v203
	v_add_u32_e32 v207, 0xfffffe00, v203
	v_add_u32_e32 v208, 0xfffffe1f, v203
	v_add_u32_e32 v209, 0xfffffe00, v178
	v_add_u32_e32 v210, 1, v206
	s_mov_b32 s2, 0
	v_mov_b32_e32 v211, 0xf149f2ca
	s_mov_b64 s[10:11], 0
	v_mov_b64_e32 v[94:95], v[78:79]
	v_mov_b64_e32 v[92:93], v[76:77]
	v_mov_b64_e32 v[90:91], v[74:75]
	v_mov_b64_e32 v[88:89], v[72:73]
	v_mov_b64_e32 v[86:87], v[70:71]
	v_mov_b64_e32 v[84:85], v[68:69]
	v_mov_b64_e32 v[82:83], v[66:67]
	v_mov_b64_e32 v[110:111], v[78:79]
	v_mov_b64_e32 v[108:109], v[76:77]
	v_mov_b64_e32 v[106:107], v[74:75]
	v_mov_b64_e32 v[104:105], v[72:73]
	v_mov_b64_e32 v[102:103], v[70:71]
	v_mov_b64_e32 v[100:101], v[68:69]
	v_mov_b64_e32 v[98:99], v[66:67]
	v_readfirstlane_b32 s28, v0
	v_readfirstlane_b32 s14, v114
	v_readfirstlane_b32 s12, v206
	v_readfirstlane_b32 s21, v203
	s_bfe_u32 s28, s28, 0x10008
	s_add_i32 s12, s12, 1
	s_mov_b32 s13, 0
	s_mov_b32 s18, 0
	s_movk_i32 s19, 0x4800
	s_mov_b32 s20, 0x9000

;     ...
;     for (int i = 0; i < nt; ++i) {
;         const int j = jn;
;         const bool more = (i + 1 < nt);
;         if (more) { jn = next(j); if (probe != 1) kv_gload<DV, HAS_V>(st, Kb, VTb, ldv, jn * 64); }
	s_cmp_lt_u32 s12, 2
	s_cbranch_scc1 .Lnw_p1
	s_waitcnt vmcnt(0)

; template <int DV, bool HAS_V>
; DI void kv_sstore(const KVStage<DV>& st, unsigned char* buf) {
;     const int tid = threadIdx.x;
;     *(u32x4*)(buf + (tid >> 3) * KP + (tid & 7) * 16) = st.k[0];
;     if (HAS_V) {
; #pragma unroll
;         for (int i = 0; i < DV / 64; ++i) {
;             const int c = tid + 512 * i, kc = c & 7; unsigned char* q = buf + KT_BYTES + (c >> 3) * VP + (kc >> 1) * 32 + (kc & 1) * 8;
;             u32x2 lo, hi; lo.x = st.v[i].x; lo.y = st.v[i].y; hi.x = st.v[i].z; hi.y = st.v[i].w;
;             *(u32x2*)q = lo; *(u32x2*)(q + 16) = hi;
;         }
;     }
; }
	v_add_u32_e32 v192, s19, v194
	v_add_u32_e32 v193, v192, v195
	v_add3_u32 v192, v192, v196, v197
	v_add_u32_e32 v192, 0x2000, v192
	ds_write_b128 v193, v[228:231]
	ds_write2_b64 v192, v[232:233], v[234:235] offset0:128 offset1:130

;     ...
;     for (int i = 0; i < nt; ++i) {
;         const int j = jn;
;         const bool more = (i + 1 < nt);
;         if (more) { jn = next(j); if (probe != 1) kv_gload<DV, HAS_V>(st, Kb, VTb, ldv, jn * 64); }
	s_cmp_lt_u32 s12, 3
	s_cbranch_scc1 .Lnw_p1
	s_add_i32 s15, s14, 2

; template <int DV, bool HAS_V>
; DI void kv_gload(KVStage<DV>& st, const bf16_t* __restrict__ Kb, const bf16_t* __restrict__ VTb, int ldv, int key0) {
;     const int tid = threadIdx.x;
;     st.k[0] = *(const u32x4*)(Kb + (size_t)(key0 + (tid >> 3)) * 64 + (tid & 7) * 8);
;     if (HAS_V) {
; #pragma unroll
;         for (int i = 0; i < DV / 64; ++i) { const int c = tid + 512 * i; st.v[i] = *(const u32x4*)(VTb + (size_t)(key0 >> 6) * (DV * 64) + c * 8); }
;     }
; }
	s_lshl_b32 s4, s15, 6
	v_add_u32_e32 v228, s4, v187
	v_mov_b32_e32 v229, v173
	v_lshlrev_b64 v[228:229], 7, v[228:229]
	v_lshl_add_u64 v[228:229], v[188:189], 0, v[228:229]
	global_load_dwordx4 v[162:165], v[228:229], off
	s_lshl_b32 s4, s15, 13
	s_mov_b32 s5, 0
	v_lshl_add_u64 v[230:231], v[190:191], 0, s[4:5]
	global_load_dwordx4 v[166:169], v[230:231], off

;     ...
;             const int k0 = j * 64;
;             if (k0 > qb + 31 || k0 + 63 <= qb - 512) return;
.Lnw_p1:
	s_lshl_b32 s6, s14, 6
	s_add_i32 s7, s21, 31
	s_cmp_le_i32 s6, s7
	s_cselect_b32 s16, 1, 0
	s_add_i32 s6, s6, 63
	s_add_i32 s7, s21, 0xfffffe00
	s_cmp_gt_i32 s6, s7
	s_cselect_b32 s7, 1, 0
	s_and_b32 s16, s16, s7

;     ...
;             const int k0 = j * 64;
;             if (k0 > qb + 31 || k0 + 63 <= qb - 512) return;
;             f32x16 s0, s1; attn_scores(sb, qf, r, h, s0, s1);
	s_cmp_eq_u32 s16, 0
	s_cbranch_scc1 .Lnw_p3
	v_add3_u32 v236, s18, v204, v180

; #define MFMA(a, b, c) __builtin_amdgcn_mfma_f32_32x32x16_bf16((a), (b), (c), 0, 0, 0)
; DI void attn_scores(const unsigned char* kb, const bf16x8 (&qf)[4], int r, int h, f32x16& s0, f32x16& s1) {
; #pragma unroll
;     for (int i = 0; i < 16; ++i) { s0[i] = 0.f; s1[i] = 0.f; }
; #pragma unroll
;     for (int s = 0; s < 4; ++s) {
;         const bf16x8 k0 = *(const bf16x8*)(kb + r * KP + s * 32 + h * 16);
;         const bf16x8 k1 = *(const bf16x8*)(kb + (32 + r) * KP + s * 32 + h * 16);
;         s0 = MFMA(k0, qf[s], s0); s1 = MFMA(k1, qf[s], s1);
;     }
; }
	ds_read_b128 v[228:231], v236 offset:0
	ds_read_b128 v[232:235], v236 offset:4608
	ds_read_b128 v[206:209], v236 offset:32
	s_waitcnt lgkmcnt(2)
	v_mfma_f32_32x32x16_bf16 v[130:145], v[228:231], v[146:149], 0
	ds_read_b128 v[228:231], v236 offset:4640
	s_waitcnt lgkmcnt(2)
	v_mfma_f32_32x32x16_bf16 v[114:129], v[232:235], v[146:149], 0
	ds_read_b128 v[232:235], v236 offset:64
	s_waitcnt lgkmcnt(2)
	v_mfma_f32_32x32x16_bf16 v[130:145], v[206:209], v[150:153], v[130:145]
	ds_read_b128 v[206:209], v236 offset:4672
	s_waitcnt lgkmcnt(2)
	v_mfma_f32_32x32x16_bf16 v[114:129], v[228:231], v[150:153], v[114:129]
	ds_read_b128 v[228:231], v236 offset:96
	s_waitcnt lgkmcnt(2)
	v_mfma_f32_32x32x16_bf16 v[130:145], v[232:235], v[154:157], v[130:145]
	ds_read_b128 v[232:235], v236 offset:4704
	s_waitcnt lgkmcnt(2)
	v_mfma_f32_32x32x16_bf16 v[114:129], v[206:209], v[154:157], v[114:129]
	s_waitcnt lgkmcnt(1)
	v_mfma_f32_32x32x16_bf16 v[130:145], v[228:231], v[158:161], v[130:145]
	s_waitcnt lgkmcnt(0)
	v_mfma_f32_32x32x16_bf16 v[114:129], v[232:235], v[158:161], v[114:129]
.Lnw_p3:
	s_waitcnt lgkmcnt(0)
	s_cmp_eq_u32 s28, 0
	s_cbranch_scc1 .Lnw_loop
	s_barrier
